# phase 3 reordered: the GLA state scan runs after the attention units instead of before them (overlaps other workgroups' attention tails)
# speedup vs baseline: 1.0090x; 1.0017x over previous
.LBB0_88:
	s_and_b64 vcc, exec, s[0:1]
	s_cbranch_vccz .LBB0_130
	v_readlane_b32 s0, v254, 36
	v_readlane_b32 s1, v254, 37
	s_lshl_b32 s0, s0, 6
	s_ashr_i32 s1, s0, 31
	v_readlane_b32 s4, v249, 56
	s_lshl_b64 s[0:1], s[0:1], 2
	v_readlane_b32 s16, v250, 4
	s_mov_b64 s[30:31], s[60:61]
	s_mov_b32 s23, s57
	s_mov_b64 s[24:25], s[62:63]
	v_readlane_b32 s17, v250, 5
	s_add_u32 s2, s16, s0
	v_readlane_b32 s48, v249, 38
	s_addc_u32 s3, s17, s1
	v_readlane_b32 s50, v249, 40
	v_readlane_b32 s5, v249, 57
	v_readlane_b32 s51, v249, 41
	s_add_u32 s4, s50, s0
	v_readlane_b32 s6, v249, 58
	v_readlane_b32 s18, v250, 6
	s_addc_u32 s5, s51, s1
	v_readlane_b32 s7, v249, 59
	v_readlane_b32 s19, v250, 7
	s_add_u32 s6, s18, s0
	v_readlane_b32 s8, v249, 60
	s_addc_u32 s7, s19, s1
	v_readlane_b32 s9, v249, 61
	v_readlane_b32 s49, v249, 39
	s_add_u32 s8, s48, s0
	v_mov_b32_e32 v0, v216
	s_addc_u32 s9, s49, s1
	s_mov_b64 s[0:1], 0
	v_mov_b32_e32 v3, 0
	s_waitcnt lgkmcnt(0)
	v_mov_b32_e32 v2, 0
	v_readlane_b32 s10, v249, 62
	v_readlane_b32 s11, v249, 63
	v_readlane_b32 s12, v250, 0
	v_readlane_b32 s13, v250, 1
	v_readlane_b32 s14, v250, 2
	v_readlane_b32 s15, v250, 3
	v_readlane_b32 s52, v249, 42
	v_readlane_b32 s53, v249, 43
	v_readlane_b32 s54, v249, 44
	v_readlane_b32 s55, v249, 45
	v_readlane_b32 s56, v249, 46
	v_readlane_b32 s57, v249, 47
	v_readlane_b32 s58, v249, 48
	v_readlane_b32 s59, v249, 49
	v_readlane_b32 s60, v249, 50
	v_readlane_b32 s61, v249, 51
	v_readlane_b32 s62, v249, 52
	v_readlane_b32 s63, v249, 53

.Lscan_late:
	v_mov_b32_e32 v0, v216
	v_readlane_b32 s0, v252, 37
	s_nop 1
	v_add_u32_e32 v54, s0, v0
	s_mov_b32 s0, 0x10000
	v_cmp_gt_i32_e32 vcc, s0, v54
	s_and_saveexec_b64 s[0:1], vcc
	s_mov_b32 s6, 0xffff
	s_cbranch_execz .LBB0_94
	s_mov_b64 s[2:3], 0
